# v16 + grid barrier: the last-arriving XCD leader bumps every XCD's local generation word itself (no per-XCD relay hop)
# speedup vs baseline: 1.0069x; 1.0069x over previous
.LBB0_194:
	s_or_b64 exec, exec, s[4:5]
	s_and_saveexec_b64 s[2:3], s[6:7]
	s_cbranch_execz .LBB0_196
	v_mov_b32_e32 v1, 1
	s_add_u32 s0, s38, 0x2400
	s_addc_u32 s1, s39, 0
	v_mov_b32_e32 v6, s0
	v_mov_b32_e32 v7, s1
	flat_atomic_add v[6:7], v1
	flat_atomic_add v[6:7], v1 offset:256
	flat_atomic_add v[6:7], v1 offset:512
	flat_atomic_add v[6:7], v1 offset:768
	flat_atomic_add v[6:7], v1 offset:1024
	flat_atomic_add v[6:7], v1 offset:1280
	flat_atomic_add v[6:7], v1 offset:1536
	flat_atomic_add v[6:7], v1 offset:1792
	flat_atomic_add v[6:7], v1 offset:2048
	flat_atomic_add v[6:7], v1 offset:2304
	flat_atomic_add v[6:7], v1 offset:2560
	flat_atomic_add v[6:7], v1 offset:2816
	flat_atomic_add v[6:7], v1 offset:3072
	flat_atomic_add v[6:7], v1 offset:3328
	flat_atomic_add v[6:7], v1 offset:3584
	flat_atomic_add v[6:7], v1 offset:3840
	flat_atomic_add v[2:3], v1
.LBB0_196:
	s_or_b64 exec, exec, s[2:3]
	s_add_i32 s0, s13, 0x900
	s_mov_b32 s1, 0
	s_lshl_b64 s[0:1], s[0:1], 2
	s_add_u32 s0, s38, s0
	s_addc_u32 s1, s39, s1
	v_mov_b32_e32 v1, 1
	v_mov_b64_e32 v[2:3], s[0:1]
	s_waitcnt vmcnt(0)

.LBB0_375:
	s_or_b64 exec, exec, s[6:7]
	s_and_saveexec_b64 s[4:5], s[8:9]
	s_cbranch_execz .LBB0_377
	v_mov_b32_e32 v1, 1
	s_add_u32 s0, s38, 0x2400
	s_addc_u32 s1, s39, 0
	v_mov_b32_e32 v6, s0
	v_mov_b32_e32 v7, s1
	flat_atomic_add v[6:7], v1
	flat_atomic_add v[6:7], v1 offset:256
	flat_atomic_add v[6:7], v1 offset:512
	flat_atomic_add v[6:7], v1 offset:768
	flat_atomic_add v[6:7], v1 offset:1024
	flat_atomic_add v[6:7], v1 offset:1280
	flat_atomic_add v[6:7], v1 offset:1536
	flat_atomic_add v[6:7], v1 offset:1792
	flat_atomic_add v[6:7], v1 offset:2048
	flat_atomic_add v[6:7], v1 offset:2304
	flat_atomic_add v[6:7], v1 offset:2560
	flat_atomic_add v[6:7], v1 offset:2816
	flat_atomic_add v[6:7], v1 offset:3072
	flat_atomic_add v[6:7], v1 offset:3328
	flat_atomic_add v[6:7], v1 offset:3584
	flat_atomic_add v[6:7], v1 offset:3840
	flat_atomic_add v[2:3], v1
.LBB0_377:
	s_or_b64 exec, exec, s[4:5]
	s_add_i32 s0, s13, 0x900
	s_mov_b32 s1, 0
	s_lshl_b64 s[0:1], s[0:1], 2
	s_add_u32 s0, s38, s0
	s_addc_u32 s1, s39, s1
	v_mov_b32_e32 v1, 1
	v_mov_b64_e32 v[2:3], s[0:1]
	s_waitcnt vmcnt(0)

.LBB0_380:
	s_or_b64 exec, exec, s[4:5]
	s_add_i32 s86, s26, 0x900
	s_lshl_b64 s[0:1], s[86:87], 2
	s_add_u32 s0, s38, s0
	s_addc_u32 s1, s39, s1
	v_mov_b64_e32 v[2:3], s[0:1]
	s_waitcnt vmcnt(0)

.LBB0_570:
	s_or_b64 exec, exec, s[6:7]
	s_and_saveexec_b64 s[4:5], s[8:9]
	s_cbranch_execz .LBB0_572
	s_add_u32 s0, s38, 0x2400
	s_addc_u32 s1, s39, 0
	v_mov_b32_e32 v6, s0
	v_mov_b32_e32 v7, s1
	flat_atomic_add v[6:7], v1
	flat_atomic_add v[6:7], v1 offset:256
	flat_atomic_add v[6:7], v1 offset:512
	flat_atomic_add v[6:7], v1 offset:768
	flat_atomic_add v[6:7], v1 offset:1024
	flat_atomic_add v[6:7], v1 offset:1280
	flat_atomic_add v[6:7], v1 offset:1536
	flat_atomic_add v[6:7], v1 offset:1792
	flat_atomic_add v[6:7], v1 offset:2048
	flat_atomic_add v[6:7], v1 offset:2304
	flat_atomic_add v[6:7], v1 offset:2560
	flat_atomic_add v[6:7], v1 offset:2816
	flat_atomic_add v[6:7], v1 offset:3072
	flat_atomic_add v[6:7], v1 offset:3328
	flat_atomic_add v[6:7], v1 offset:3584
	flat_atomic_add v[6:7], v1 offset:3840
	flat_atomic_add v[2:3], v1

.LBB0_620:
	s_or_b64 exec, exec, s[4:5]
	s_and_saveexec_b64 s[2:3], s[6:7]
	s_cbranch_execz .LBB0_622
	s_add_u32 s0, s38, 0x2400
	s_addc_u32 s1, s39, 0
	v_mov_b32_e32 v6, s0
	v_mov_b32_e32 v7, s1
	flat_atomic_add v[6:7], v1
	flat_atomic_add v[6:7], v1 offset:256
	flat_atomic_add v[6:7], v1 offset:512
	flat_atomic_add v[6:7], v1 offset:768
	flat_atomic_add v[6:7], v1 offset:1024
	flat_atomic_add v[6:7], v1 offset:1280
	flat_atomic_add v[6:7], v1 offset:1536
	flat_atomic_add v[6:7], v1 offset:1792
	flat_atomic_add v[6:7], v1 offset:2048
	flat_atomic_add v[6:7], v1 offset:2304
	flat_atomic_add v[6:7], v1 offset:2560
	flat_atomic_add v[6:7], v1 offset:2816
	flat_atomic_add v[6:7], v1 offset:3072
	flat_atomic_add v[6:7], v1 offset:3328
	flat_atomic_add v[6:7], v1 offset:3584
	flat_atomic_add v[6:7], v1 offset:3840
	flat_atomic_add v[2:3], v1
.LBB0_622:
	s_or_b64 exec, exec, s[2:3]
	s_add_i32 s86, s24, 0x900
	s_lshl_b64 s[0:1], s[86:87], 2
	s_add_u32 s0, s38, s0
	s_addc_u32 s1, s39, s1
	v_mov_b64_e32 v[2:3], s[0:1]
	s_waitcnt vmcnt(0)

.LBB0_949:
	s_or_b64 exec, exec, s[8:9]
	s_and_saveexec_b64 s[6:7], s[10:11]
	s_cbranch_execz .LBB0_951
	s_add_u32 s0, s2, 0x2400
	s_addc_u32 s1, s3, 0
	v_mov_b32_e32 v6, s0
	v_mov_b32_e32 v7, s1
	flat_atomic_add v[6:7], v1
	flat_atomic_add v[6:7], v1 offset:256
	flat_atomic_add v[6:7], v1 offset:512
	flat_atomic_add v[6:7], v1 offset:768
	flat_atomic_add v[6:7], v1 offset:1024
	flat_atomic_add v[6:7], v1 offset:1280
	flat_atomic_add v[6:7], v1 offset:1536
	flat_atomic_add v[6:7], v1 offset:1792
	flat_atomic_add v[6:7], v1 offset:2048
	flat_atomic_add v[6:7], v1 offset:2304
	flat_atomic_add v[6:7], v1 offset:2560
	flat_atomic_add v[6:7], v1 offset:2816
	flat_atomic_add v[6:7], v1 offset:3072
	flat_atomic_add v[6:7], v1 offset:3328
	flat_atomic_add v[6:7], v1 offset:3584
	flat_atomic_add v[6:7], v1 offset:3840
	flat_atomic_add v[2:3], v1
.LBB0_951:
	s_or_b64 exec, exec, s[6:7]
	s_add_i32 s86, s28, 0x900
	s_lshl_b64 s[0:1], s[86:87], 2
	s_add_u32 s0, s2, s0
	s_addc_u32 s1, s3, s1
	v_mov_b64_e32 v[2:3], s[0:1]
	s_waitcnt vmcnt(0)

.LBB0_1038:
	s_or_b64 exec, exec, s[10:11]
	s_and_saveexec_b64 s[8:9], s[14:15]
	s_cbranch_execz .LBB0_1040
	s_add_u32 s0, s4, 0x2400
	s_addc_u32 s1, s5, 0
	v_mov_b32_e32 v6, s0
	v_mov_b32_e32 v7, s1
	flat_atomic_add v[6:7], v1
	flat_atomic_add v[6:7], v1 offset:256
	flat_atomic_add v[6:7], v1 offset:512
	flat_atomic_add v[6:7], v1 offset:768
	flat_atomic_add v[6:7], v1 offset:1024
	flat_atomic_add v[6:7], v1 offset:1280
	flat_atomic_add v[6:7], v1 offset:1536
	flat_atomic_add v[6:7], v1 offset:1792
	flat_atomic_add v[6:7], v1 offset:2048
	flat_atomic_add v[6:7], v1 offset:2304
	flat_atomic_add v[6:7], v1 offset:2560
	flat_atomic_add v[6:7], v1 offset:2816
	flat_atomic_add v[6:7], v1 offset:3072
	flat_atomic_add v[6:7], v1 offset:3328
	flat_atomic_add v[6:7], v1 offset:3584
	flat_atomic_add v[6:7], v1 offset:3840
	flat_atomic_add v[2:3], v1
.LBB0_1040:
	s_or_b64 exec, exec, s[8:9]
	s_add_i32 s86, s30, 0x900
	s_lshl_b64 s[0:1], s[86:87], 2
	s_add_u32 s0, s4, s0
	s_addc_u32 s1, s5, s1
	v_mov_b64_e32 v[2:3], s[0:1]
	s_waitcnt vmcnt(0)

.LBB0_1294:
	s_or_b64 exec, exec, s[14:15]
	s_and_saveexec_b64 s[10:11], s[16:17]
	s_cbranch_execz .LBB0_1296
	s_add_u32 s0, s4, 0x2400
	s_addc_u32 s1, s5, 0
	v_mov_b32_e32 v6, s0
	v_mov_b32_e32 v7, s1
	flat_atomic_add v[6:7], v1
	flat_atomic_add v[6:7], v1 offset:256
	flat_atomic_add v[6:7], v1 offset:512
	flat_atomic_add v[6:7], v1 offset:768
	flat_atomic_add v[6:7], v1 offset:1024
	flat_atomic_add v[6:7], v1 offset:1280
	flat_atomic_add v[6:7], v1 offset:1536
	flat_atomic_add v[6:7], v1 offset:1792
	flat_atomic_add v[6:7], v1 offset:2048
	flat_atomic_add v[6:7], v1 offset:2304
	flat_atomic_add v[6:7], v1 offset:2560
	flat_atomic_add v[6:7], v1 offset:2816
	flat_atomic_add v[6:7], v1 offset:3072
	flat_atomic_add v[6:7], v1 offset:3328
	flat_atomic_add v[6:7], v1 offset:3584
	flat_atomic_add v[6:7], v1 offset:3840
	flat_atomic_add v[2:3], v1
.LBB0_1296:
	s_or_b64 exec, exec, s[10:11]
	s_add_i32 s86, s34, 0x900
	s_lshl_b64 s[0:1], s[86:87], 2
	s_add_u32 s0, s4, s0
	s_addc_u32 s1, s5, s1
	v_mov_b64_e32 v[2:3], s[0:1]
	s_waitcnt vmcnt(0)

.LBB0_1860:
	s_add_u32 s0, s38, 0x2400
	s_addc_u32 s1, s39, 0
	v_mov_b32_e32 v6, s0
	v_mov_b32_e32 v7, s1
	flat_atomic_add v[6:7], v1
	flat_atomic_add v[6:7], v1 offset:256
	flat_atomic_add v[6:7], v1 offset:512
	flat_atomic_add v[6:7], v1 offset:768
	flat_atomic_add v[6:7], v1 offset:1024
	flat_atomic_add v[6:7], v1 offset:1280
	flat_atomic_add v[6:7], v1 offset:1536
	flat_atomic_add v[6:7], v1 offset:1792
	flat_atomic_add v[6:7], v1 offset:2048
	flat_atomic_add v[6:7], v1 offset:2304
	flat_atomic_add v[6:7], v1 offset:2560
	flat_atomic_add v[6:7], v1 offset:2816
	flat_atomic_add v[6:7], v1 offset:3072
	flat_atomic_add v[6:7], v1 offset:3328
	flat_atomic_add v[6:7], v1 offset:3584
	flat_atomic_add v[6:7], v1 offset:3840
	flat_atomic_add v[2:3], v1
	s_getpc_b64 s[98:99]
